# GQA loop: all 8 K-fragment LDS reads issued right after the tile barrier into separate buffers (on top of v5)
# speedup vs baseline: 1.0041x; 1.0003x over previous
; __device__ __forceinline__ float fexp2(float x) { return __builtin_amdgcn_exp2f(x); }
; template <int DQK, int DV>
; __device__ __forceinline__ void attn_pass2(const bf16_t* __restrict__ qh, const bf16_t* __restrict__ kh, const bf16_t* __restrict__ vth, int q0, char* smem, f32x16 (&o)[2][DV / 32], float kmax, int wvp) {
;     ...
;   for (int kt = 0; kt < NT; ++kt) {
;     const int cur = kt & 1;
;     __syncthreads();
;     if (kt + 1 < NT) { STOREKV(cur ^ 1); if (kt + 2 < NT) LOADKV(kt + 2); }
;     f32x16 s[2][2];
;     const char* kb0 = sK + cur * KSB + kofs;
; #pragma unroll
;     for (int ks = 0; ks < NKS; ++ks) {
;       const bf16x8 a0 = *(const bf16x8*)(kb0 + ks * 32), a1 = *(const bf16x8*)(kb0 + 32 * KP + ks * 32);
; #pragma unroll
;       for (int qb = 0; qb < 2; ++qb) {
;         if (ks == 0) {
;           f32x16 z;
; #pragma unroll
;           for (int i = 0; i < 16; ++i) z[i] = 0.f;
;           s[qb][0] = MFMA(a0, qf[qb][0], z); s[qb][1] = MFMA(a1, qf[qb][0], z);
;         } else { s[qb][0] = MFMA(a0, qf[qb][ks], s[qb][0]); s[qb][1] = MFMA(a1, qf[qb][ks], s[qb][1]); }
;       }
;     }
;     __builtin_amdgcn_sched_barrier(0);
; #pragma unroll
;     for (int qb = 0; qb < 2; ++qb) {
;       float rs0 = 0.f, rs1 = 0.f;
; #pragma unroll
;       for (int i = 0; i < 16; ++i) { s[qb][0][i] = fexp2(s[qb][0][i] - mref[qb]); s[qb][1][i] = fexp2(s[qb][1][i] - mref[qb]); rs0 += s[qb][0][i]; rs1 += s[qb][1][i]; }
;       l_run[qb] += rs0 + rs1;
;     }
;     const char* vb0 = sV + cur * VSB + vofs;
; #pragma unroll
;     for (int kb = 0; kb < 2; ++kb)
; #pragma unroll
;       for (int s2 = 0; s2 < 2; ++s2) {
;         bf16x8 pq[2];
; #pragma unroll
;         for (int qb = 0; qb < 2; ++qb) {
;           u32x4 w;
;           w.x = pk2(s[qb][kb][8 * s2 + 0], s[qb][kb][8 * s2 + 1]); w.y = pk2(s[qb][kb][8 * s2 + 2], s[qb][kb][8 * s2 + 3]);
;           w.z = pk2(s[qb][kb][8 * s2 + 4], s[qb][kb][8 * s2 + 5]); w.w = pk2(s[qb][kb][8 * s2 + 6], s[qb][kb][8 * s2 + 7]);
;           pq[qb] = __builtin_bit_cast(bf16x8, w);
;         }
; #pragma unroll
;         for (int eb = 0; eb < NEB; ++eb) {
;           const bf16x8 a = *(const bf16x8*)(vb0 + eb * 32 * VP + (32 * kb + 16 * s2) * 2);
; #pragma unroll
;           for (int qb = 0; qb < 2; ++qb) o[qb][eb] = MFMA(a, pq[qb], o[qb][eb]);
;         }
;       }
;   }
.LBB0_1429:
	s_mulk_i32 s7, 0x2400
	s_add_i32 s6, s6, 1
	s_waitcnt lgkmcnt(7)
	v_mfma_f32_32x32x16_bf16 v[112:127], v[64:67], v[128:131], v[236:251]
	s_waitcnt lgkmcnt(5)
	v_mfma_f32_32x32x16_bf16 v[96:111], v[68:71], v[128:131], v[236:251]
	v_mfma_f32_32x32x16_bf16 v[80:95], v[64:67], v[144:147], v[236:251]
	v_mfma_f32_32x32x16_bf16 v[64:79], v[68:71], v[144:147], v[236:251]
	v_mfma_f32_32x32x16_bf16 v[112:127], v[176:179], v[132:135], v[112:127]
	s_waitcnt lgkmcnt(4)
	v_mfma_f32_32x32x16_bf16 v[96:111], v[192:195], v[132:135], v[96:111]
	v_mfma_f32_32x32x16_bf16 v[80:95], v[176:179], v[148:151], v[80:95]
	v_mfma_f32_32x32x16_bf16 v[64:79], v[192:195], v[148:151], v[64:79]
	s_waitcnt lgkmcnt(3)
	v_mfma_f32_32x32x16_bf16 v[112:127], v[216:219], v[136:139], v[112:127]
	s_waitcnt lgkmcnt(1)
	v_mfma_f32_32x32x16_bf16 v[96:111], v[196:199], v[136:139], v[96:111]
	v_mfma_f32_32x32x16_bf16 v[80:95], v[216:219], v[152:155], v[80:95]
	v_mfma_f32_32x32x16_bf16 v[64:79], v[196:199], v[152:155], v[64:79]
	v_mfma_f32_32x32x16_bf16 v[112:127], v[220:223], v[140:143], v[112:127]
	s_waitcnt lgkmcnt(0)
	v_mfma_f32_32x32x16_bf16 v[96:111], v[200:203], v[140:143], v[96:111]
	v_mfma_f32_32x32x16_bf16 v[80:95], v[220:223], v[156:159], v[80:95]
	v_mfma_f32_32x32x16_bf16 v[64:79], v[200:203], v[156:159], v[64:79]
	s_nop 9
	v_exp_f32_e32 v186, v96
	v_exp_f32_e32 v97, v97
	v_exp_f32_e32 v177, v112
	v_exp_f32_e32 v113, v113
	v_exp_f32_e32 v179, v114
	v_exp_f32_e32 v187, v98
	v_add_f32_e32 v98, v97, v186
	v_exp_f32_e32 v115, v115
	v_exp_f32_e32 v190, v99
	v_exp_f32_e32 v204, v100
	v_exp_f32_e32 v99, v116
	v_exp_f32_e32 v117, v117
	v_add_f32_e32 v96, v113, v177
	v_exp_f32_e32 v101, v101
	v_add_f32_e32 v96, v179, v96
	v_exp_f32_e32 v181, v118
	v_add_f32_e32 v96, v115, v96
	v_add_f32_e32 v96, v99, v96
	v_add_f32_e32 v96, v117, v96
	v_add_f32_e32 v112, v181, v96
	v_exp_f32_e32 v176, v119
	v_exp_f32_e32 v178, v103
	v_add_f32_e32 v98, v187, v98
	v_exp_f32_e32 v205, v102
	v_exp_f32_e32 v180, v120
	v_exp_f32_e32 v96, v104
	v_exp_f32_e32 v104, v123
	v_add_f32_e32 v98, v190, v98
	v_exp_f32_e32 v100, v106
	v_exp_f32_e32 v106, v107
	v_add_f32_e32 v98, v204, v98
	v_exp_f32_e32 v118, v124
	v_add_f32_e32 v98, v101, v98
	v_exp_f32_e32 v120, v108
	v_add_f32_e32 v102, v205, v98
	v_exp_f32_e32 v124, v125
	v_exp_f32_e32 v116, v121
	v_exp_f32_e32 v108, v109
	v_exp_f32_e32 v114, v105
	v_exp_f32_e32 v98, v122
	v_exp_f32_e32 v122, v126
	v_exp_f32_e32 v110, v110
	v_exp_f32_e32 v126, v127
	v_exp_f32_e32 v103, v80
	v_exp_f32_e32 v107, v64
	v_exp_f32_e32 v109, v81
	v_exp_f32_e32 v65, v65
	v_exp_f32_e32 v121, v66
	v_add_f32_e32 v66, v109, v103
	v_add_f32_e32 v80, v65, v107
	v_add_f32_e32 v206, v121, v80
	v_exp_f32_e32 v207, v83
	v_add_u32_e32 v209, s7, v185
	v_exp_f32_e32 v64, v111
	v_exp_f32_e32 v111, v82
	v_exp_f32_e32 v208, v84
	ds_read_b128 v[80:83], v209 offset:18432
	ds_read_b128 v[196:199], v209 offset:18464
	ds_read_b128 v[200:203], v209 offset:23040
	v_exp_f32_e32 v212, v85
	v_exp_f32_e32 v213, v86
	v_cvt_pk_bf16_f32 v192, v177, v113
	v_exp_f32_e32 v177, v87
	v_cvt_pk_bf16_f32 v84, v103, v109
	v_exp_f32_e32 v109, v67
	v_add_f32_e32 v66, v111, v66
	v_cvt_pk_bf16_f32 v85, v111, v207
	v_exp_f32_e32 v111, v68
	v_cvt_pk_bf16_f32 v195, v181, v176
	v_exp_f32_e32 v181, v88
	v_cvt_pk_bf16_f32 v194, v99, v117
	v_exp_f32_e32 v117, v89
	v_cvt_pk_bf16_f32 v193, v179, v115
	v_cvt_pk_bf16_f32 v86, v208, v212
	v_cvt_pk_bf16_f32 v87, v213, v177
	v_exp_f32_e32 v99, v90
	s_waitcnt lgkmcnt(2)
	v_mfma_f32_32x32x16_bf16 v[48:63], v[80:83], v[192:195], v[48:63]
	v_exp_f32_e32 v105, v91
	v_exp_f32_e32 v119, v92
	v_exp_f32_e32 v125, v93
	v_mfma_f32_32x32x16_bf16 v[16:31], v[80:83], v[84:87], v[16:31]
	ds_read_b128 v[80:83], v209 offset:23072
	v_exp_f32_e32 v123, v94
	v_exp_f32_e32 v92, v69
	v_exp_f32_e32 v127, v95
	s_waitcnt lgkmcnt(1)
; __device__ __forceinline__ float fexp2(float x) { return __builtin_amdgcn_exp2f(x); }
; template <int DQK, int DV>
; __device__ __forceinline__ void attn_pass2(const bf16_t* __restrict__ qh, const bf16_t* __restrict__ kh, const bf16_t* __restrict__ vth, int q0, char* smem, f32x16 (&o)[2][DV / 32], float kmax, int wvp) {
;     ...
;   for (int kt = 0; kt < NT; ++kt) {
;     const int cur = kt & 1;
;     __syncthreads();
;     if (kt + 1 < NT) { STOREKV(cur ^ 1); if (kt + 2 < NT) LOADKV(kt + 2); }
;     f32x16 s[2][2];
;     const char* kb0 = sK + cur * KSB + kofs;
; #pragma unroll
;     for (int ks = 0; ks < NKS; ++ks) {
;       const bf16x8 a0 = *(const bf16x8*)(kb0 + ks * 32), a1 = *(const bf16x8*)(kb0 + 32 * KP + ks * 32);
; #pragma unroll
;       for (int qb = 0; qb < 2; ++qb) {
;         if (ks == 0) {
;           f32x16 z;
; #pragma unroll
;           for (int i = 0; i < 16; ++i) z[i] = 0.f;
;           s[qb][0] = MFMA(a0, qf[qb][0], z); s[qb][1] = MFMA(a1, qf[qb][0], z);
;         } else { s[qb][0] = MFMA(a0, qf[qb][ks], s[qb][0]); s[qb][1] = MFMA(a1, qf[qb][ks], s[qb][1]); }
;       }
;     }
;     __builtin_amdgcn_sched_barrier(0);
; #pragma unroll
;     for (int qb = 0; qb < 2; ++qb) {
;       float rs0 = 0.f, rs1 = 0.f;
; #pragma unroll
;       for (int i = 0; i < 16; ++i) { s[qb][0][i] = fexp2(s[qb][0][i] - mref[qb]); s[qb][1][i] = fexp2(s[qb][1][i] - mref[qb]); rs0 += s[qb][0][i]; rs1 += s[qb][1][i]; }
;       l_run[qb] += rs0 + rs1;
;     }
;     const char* vb0 = sV + cur * VSB + vofs;
; #pragma unroll
;     for (int kb = 0; kb < 2; ++kb)
; #pragma unroll
;       for (int s2 = 0; s2 < 2; ++s2) {
;         bf16x8 pq[2];
; #pragma unroll
;         for (int qb = 0; qb < 2; ++qb) {
;           u32x4 w;
;           w.x = pk2(s[qb][kb][8 * s2 + 0], s[qb][kb][8 * s2 + 1]); w.y = pk2(s[qb][kb][8 * s2 + 2], s[qb][kb][8 * s2 + 3]);
;           w.z = pk2(s[qb][kb][8 * s2 + 4], s[qb][kb][8 * s2 + 5]); w.w = pk2(s[qb][kb][8 * s2 + 6], s[qb][kb][8 * s2 + 7]);
;           pq[qb] = __builtin_bit_cast(bf16x8, w);
;         }
; #pragma unroll
;         for (int eb = 0; eb < NEB; ++eb) {
;           const bf16x8 a = *(const bf16x8*)(vb0 + eb * 32 * VP + (32 * kb + 16 * s2) * 2);
; #pragma unroll
;           for (int qb = 0; qb < 2; ++qb) o[qb][eb] = MFMA(a, pq[qb], o[qb][eb]);
;         }
;       }
;   }
	v_mfma_f32_32x32x16_bf16 v[0:15], v[200:203], v[84:87], v[0:15]
	v_exp_f32_e32 v93, v70
	v_add_f32_e32 v66, v207, v66
	v_add_f32_e32 v67, v109, v206
	v_add_f32_e32 v66, v208, v66
	v_add_f32_e32 v67, v111, v67
	v_add_f32_e32 v66, v212, v66
	v_add_f32_e32 v67, v92, v67
	v_mfma_f32_32x32x16_bf16 v[32:47], v[200:203], v[192:195], v[32:47]
	v_cvt_pk_bf16_f32 v84, v180, v116
	v_cvt_pk_bf16_f32 v85, v98, v104
	v_cvt_pk_bf16_f32 v86, v118, v124
	v_cvt_pk_bf16_f32 v87, v122, v126
	v_cvt_pk_bf16_f32 v88, v181, v117
	v_cvt_pk_bf16_f32 v89, v99, v105
	v_cvt_pk_bf16_f32 v90, v119, v125
	v_cvt_pk_bf16_f32 v91, v123, v127
	v_add_f32_e32 v113, v213, v66
	v_add_f32_e32 v103, v93, v67
	ds_read_b128 v[66:69], v209 offset:18496
	v_mfma_f32_32x32x16_bf16 v[48:63], v[196:199], v[84:87], v[48:63]
	v_exp_f32_e32 v179, v71
	v_mov_b32_e32 v70, v72
	v_exp_f32_e32 v115, v73
	v_cvt_pk_bf16_f32 v71, v121, v109
	v_cvt_pk_bf16_f32 v72, v111, v92
	v_cvt_pk_bf16_f32 v73, v93, v179
	v_mfma_f32_32x32x16_bf16 v[16:31], v[196:199], v[88:91], v[16:31]
	v_lshl_add_u64 v[170:171], v[170:171], 0, s[52:53]
	s_cmpk_lg_i32 s6, 0x80
	v_lshl_add_u64 v[172:173], v[172:173], 0, s[54:55]
	s_waitcnt lgkmcnt(1)
	v_mfma_f32_32x32x16_bf16 v[0:15], v[80:83], v[88:91], v[0:15]
	ds_read_b128 v[88:91], v209 offset:23104
	v_mfma_f32_32x32x16_bf16 v[32:47], v[80:83], v[84:87], v[32:47]
	v_cvt_pk_bf16_f32 v80, v186, v97
	v_exp_f32_e32 v97, v70
	v_cvt_pk_bf16_f32 v70, v107, v65
	v_cvt_pk_bf16_f32 v81, v187, v190
	v_cvt_pk_bf16_f32 v82, v204, v101
	v_cvt_pk_bf16_f32 v83, v205, v178
	v_exp_f32_e32 v101, v74
	ds_read_b128 v[84:87], v209 offset:18528
	s_waitcnt lgkmcnt(2)
	v_mfma_f32_32x32x16_bf16 v[48:63], v[66:69], v[80:83], v[48:63]
	v_exp_f32_e32 v107, v75
	v_exp_f32_e32 v121, v76
	v_exp_f32_e32 v109, v77
	v_exp_f32_e32 v111, v78
	v_mfma_f32_32x32x16_bf16 v[16:31], v[66:69], v[70:73], v[16:31]
	ds_read_b128 v[66:69], v209 offset:23136
	v_exp_f32_e32 v65, v79
	v_add_f32_e32 v74, v178, v102
	v_add_f32_e32 v75, v179, v103
	s_nop 0
	v_add_f32_e32 v74, v96, v74
	v_add_f32_e32 v75, v97, v75
	s_waitcnt lgkmcnt(2)
	v_mfma_f32_32x32x16_bf16 v[32:47], v[88:91], v[80:83], v[32:47]
	v_add_f32_e64 v80, v114, v74
	v_add_f32_e64 v81, v115, v75
	v_cvt_pk_bf16_f32 v74, v97, v115
	v_cvt_pk_bf16_f32 v75, v101, v107
	v_add_f32_e64 v80, v100, v80
	v_add_f32_e64 v81, v101, v81
	v_add_f32_e32 v80, v106, v80
	v_add_f32_e32 v81, v107, v81
	v_mfma_f32_32x32x16_bf16 v[0:15], v[88:91], v[70:73], v[0:15]
	v_add_f32_e64 v70, v176, v112
	v_add_f32_e64 v71, v177, v113
	v_cvt_pk_bf16_f32 v72, v120, v108
	v_add_f32_e64 v76, v180, v70
	v_add_f32_e64 v77, v181, v71
	v_cvt_pk_bf16_f32 v70, v96, v114
	v_cvt_pk_bf16_f32 v71, v100, v106
	v_cvt_pk_bf16_f32 v73, v110, v64
	v_add_f32_e32 v78, v116, v76
	v_add_f32_e32 v79, v117, v77
	v_cvt_pk_bf16_f32 v76, v121, v109
	v_cvt_pk_bf16_f32 v77, v111, v65
	s_waitcnt lgkmcnt(1)
	v_mfma_f32_32x32x16_bf16 v[48:63], v[84:87], v[70:73], v[48:63]
	v_add_f32_e64 v78, v98, v78
	v_add_f32_e64 v79, v99, v79
	v_add_f32_e64 v80, v120, v80
	v_add_f32_e64 v81, v121, v81
	v_add_f32_e64 v78, v104, v78
	v_add_f32_e64 v79, v105, v79
	v_add_f32_e32 v78, v118, v78
	v_add_f32_e32 v79, v119, v79
	s_nop 0
	v_add_f32_e32 v78, v124, v78
	v_add_f32_e32 v79, v125, v79
	v_mfma_f32_32x32x16_bf16 v[16:31], v[84:87], v[74:77], v[16:31]
	s_waitcnt lgkmcnt(0)
	v_mfma_f32_32x32x16_bf16 v[32:47], v[66:69], v[70:73], v[32:47]
	v_add_f32_e64 v70, v108, v80
	v_add_f32_e64 v71, v109, v81
	v_add_f32_e64 v72, v122, v78
	v_add_f32_e64 v73, v123, v79
	v_add_f32_e64 v70, v110, v70
	v_add_f32_e64 v71, v111, v71
	v_add_f32_e32 v72, v126, v72
	v_add_f32_e32 v73, v127, v73
	v_add_f32_e32 v64, v64, v70
	v_add_f32_e32 v65, v65, v71
	s_nop 0
	v_add_f32_e32 v64, v72, v64
	v_add_f32_e32 v65, v73, v65
	v_mfma_f32_32x32x16_bf16 v[0:15], v[66:69], v[74:77], v[0:15]
	v_add_f32_e64 v174, v174, v64
	v_add_f32_e64 v175, v175, v65
	s_cbranch_scc0 .LBB0_1433
.LBB0_1430:
	s_and_b32 s7, s6, 1
	s_cmpk_eq_i32 s6, 0x7f
	s_waitcnt lgkmcnt(0)
	s_barrier
	s_mul_i32 s98, s7, 0x2400
	v_add_u32_e32 v180, s98, v169
	ds_read_b128 v[64:67], v180
	ds_read_b128 v[176:179], v180 offset:32
	ds_read_b128 v[68:71], v180 offset:4608
	ds_read_b128 v[192:195], v180 offset:4640
	ds_read_b128 v[216:219], v180 offset:64
	ds_read_b128 v[220:223], v180 offset:96
	ds_read_b128 v[196:199], v180 offset:4672
	ds_read_b128 v[200:203], v180 offset:4704
	s_cbranch_scc1 .LBB0_1429
	s_xor_b32 s8, s7, 1
	s_mulk_i32 s8, 0x2400
	v_add_u32_e32 v214, s8, v184
	s_waitcnt vmcnt(1)
	ds_write_b128 v214, v[160:163]
	v_add_u32_e32 v214, s8, v168
	s_cmpk_gt_u32 s6, 0x7d
	s_waitcnt vmcnt(0)
	ds_write_b128 v214, v[164:167] offset:18432
	s_cbranch_scc1 .LBB0_1429
	global_load_dwordx4 v[160:163], v[170:171], off
	global_load_dwordx4 v[164:167], v[172:173], off
	s_branch .LBB0_1429

; __global__ void __launch_bounds__(512, 2) mega_fwd(Params p_arg) {
;   typedef const __attribute__((address_space(4))) Params* KParamsPtr;
;   KParamsPtr pptr = (KParamsPtr)__builtin_amdgcn_kernarg_segment_ptr(); asm volatile("" : "+s"(pptr));
;   const __attribute__((address_space(4))) Params& p = *pptr;
;   __shared__ __attribute__((aligned(16))) char smem[147456 + 16];
	.amdhsa_kernel _Z8mega_fwd6Params
		.amdhsa_group_segment_fixed_size 147472
		.amdhsa_private_segment_fixed_size 0
		.amdhsa_kernarg_size 528
		.amdhsa_user_sgpr_count 2
		.amdhsa_user_sgpr_dispatch_ptr 0
		.amdhsa_user_sgpr_queue_ptr 0
		.amdhsa_user_sgpr_kernarg_segment_ptr 1
		.amdhsa_user_sgpr_dispatch_id 0
		.amdhsa_user_sgpr_kernarg_preload_length 0
		.amdhsa_user_sgpr_kernarg_preload_offset 0
		.amdhsa_user_sgpr_private_segment_size 0
		.amdhsa_uses_dynamic_stack 0
		.amdhsa_enable_private_segment 0
		.amdhsa_system_sgpr_workgroup_id_x 1
		.amdhsa_system_sgpr_workgroup_id_y 0
		.amdhsa_system_sgpr_workgroup_id_z 0
		.amdhsa_system_sgpr_workgroup_info 0
		.amdhsa_system_vgpr_workitem_id 2
		.amdhsa_next_free_vgpr 253
		.amdhsa_next_free_sgpr 100
		.amdhsa_accum_offset 256
		.amdhsa_reserve_vcc 1
		.amdhsa_float_round_mode_32 0
		.amdhsa_float_round_mode_16_64 0
		.amdhsa_float_denorm_mode_32 3
		.amdhsa_float_denorm_mode_16_64 3
		.amdhsa_dx10_clamp 1
		.amdhsa_ieee_mode 1
		.amdhsa_fp16_overflow 0
		.amdhsa_tg_split 0
		.amdhsa_exception_fp_ieee_invalid_op 0
		.amdhsa_exception_fp_denorm_src 0
		.amdhsa_exception_fp_ieee_div_zero 0
		.amdhsa_exception_fp_ieee_overflow 0
		.amdhsa_exception_fp_ieee_underflow 0
		.amdhsa_exception_fp_ieee_inexact 0
		.amdhsa_exception_int_div_zero 0
	.end_amdhsa_kernel

; __global__ void __launch_bounds__(512, 2) mega_fwd(Params p_arg) {
;   typedef const __attribute__((address_space(4))) Params* KParamsPtr;
;   KParamsPtr pptr = (KParamsPtr)__builtin_amdgcn_kernarg_segment_ptr(); asm volatile("" : "+s"(pptr));
;   const __attribute__((address_space(4))) Params& p = *pptr;
;   __shared__ __attribute__((aligned(16))) char smem[147456 + 16];
amdhsa.kernels:
  - .agpr_count:     0
    .args:
      - .offset:         0
        .size:           272
        .value_kind:     by_value
      - .offset:         272
        .size:           4
        .value_kind:     hidden_block_count_x
      - .offset:         276
        .size:           4
        .value_kind:     hidden_block_count_y
      - .offset:         280
        .size:           4
        .value_kind:     hidden_block_count_z
      - .offset:         284
        .size:           2
        .value_kind:     hidden_group_size_x
      - .offset:         286
        .size:           2
        .value_kind:     hidden_group_size_y
      - .offset:         288
        .size:           2
        .value_kind:     hidden_group_size_z
      - .offset:         290
        .size:           2
        .value_kind:     hidden_remainder_x
      - .offset:         292
        .size:           2
        .value_kind:     hidden_remainder_y
      - .offset:         294
        .size:           2
        .value_kind:     hidden_remainder_z
      - .offset:         312
        .size:           8
        .value_kind:     hidden_global_offset_x
      - .offset:         320
        .size:           8
        .value_kind:     hidden_global_offset_y
      - .offset:         328
        .size:           8
        .value_kind:     hidden_global_offset_z
      - .offset:         336
        .size:           2
        .value_kind:     hidden_grid_dims
      - .offset:         360
        .size:           8
        .value_kind:     hidden_multigrid_sync_arg
    .group_segment_fixed_size: 147472
    .kernarg_segment_align: 8
    .kernarg_segment_size: 528
    .language:       OpenCL C
    .language_version:
      - 2
      - 0
    .max_flat_workgroup_size: 512
    .name:           _Z8mega_fwd6Params
    .private_segment_fixed_size: 0
    .sgpr_count:     106
    .sgpr_spill_count: 35
    .symbol:         _Z8mega_fwd6Params.kd
    .uniform_work_group_size: 1
    .uses_dynamic_stack: false
    .vgpr_count:     253
    .vgpr_spill_count: 0
    .wavefront_size: 64
